# P0b work balance: gu_strips unit index rotated so WGs 80..255 take the third unit, W_in convert wave index rotated by 448 so the per-wave extras of the back-to-back P0b loops no longer pile on the sam
# baseline (speedup 1.0000x reference)
; #define LAS __attribute__((address_space(3)))
; __device__ __forceinline__ void p0_decode(Frame& F, int it, P0Desc& d) {
;     unsigned char* ws = F.ws; int r = it; d.gain = nullptr; d.mode = 0; d.bj = 0;
;     if (r < 4 * P0_I_GU) { const int q = r / P0_I_GU; r -= q * P0_I_GU; d.k0 = 64 * (r / 172); d.n0 = 64 * (r % 172); d.K = DM; d.ldt = 0; d.N = FF; d.mode = 2; d.bj = q & 1;
;         d.W = q == 0 ? INP(2) : q == 1 ? INP(3) : q == 2 ? INP(18) : INP(19); d.gain = q < 2 ? INP(1) : INP(17); d.WT = (bf16_t*)(ws + (q < 2 ? WS_WGU1 : WS_WGU2)); return; }
;     r -= 4 * P0_I_GU;
;     if (r < 2 * P0_I_D) { const int q = r / P0_I_D; r -= q * P0_I_D; d.k0 = 64 * (r / 64); d.n0 = 64 * (r % 64); d.K = FF; d.ldt = 0; d.N = DM; d.W = q == 0 ? INP(4) : INP(20); d.WT = (bf16_t*)(ws + (q == 0 ? WS_WD1 : WS_WD2)); return; }
;     r -= 2 * P0_I_D;
;     if (r < P0_I_IN) { d.k0 = 64 * (r / 113); d.n0 = 64 * (r % 113); d.K = DM; d.ldt = 0; d.N = NIN; d.mode = 1; d.W = INP(6); d.gain = INP(5); d.WT = (bf16_t*)(ws + WS_WIN); return; }
; __device__ __forceinline__ void p0_convert(Frame& F, int lo, int hi, int worker, int nworkers) {
;     const int lane = (F.tid & 63), stride = nworkers * 8, first = lo + worker * 8 + F.wave;
;     LAS unsigned* T = (LAS unsigned*)(F.lds + F.wave * 16384);
;     if (first >= hi) return;
;     const int n_my = (hi - first + stride - 1) / stride;
;     f32x4 va[16], vb[16]; float ga, gb; P0Desc da, db;
;     p0_decode(F, first, da); p0_load(va, ga, da, lane);
.LBB0_159:
	s_or_b64 exec, exec, s[0:1]
	s_lshl_b32 s0, s68, 14
	s_mov_b32 s98, s10
	s_cmp_eq_u32 s71, 0x100
	s_cbranch_scc0 .Lmy_bal5
	s_add_i32 s98, s10, 0x1c0
	s_and_b32 s98, s98, 0x7ff
.Lmy_bal5:
	s_add_i32 s11, s98, 0x10200
	s_add_i32 s33, s0, 0
	s_cmp_gt_i32 s11, 0x11e3f
	s_waitcnt lgkmcnt(0)
	s_barrier
	s_cbranch_scc1 .LBB0_543
	s_abs_i32 s4, s12
	v_cvt_f32_u32_e32 v2, s4
	s_sub_i32 s0, s12, s98
	s_add_i32 s7, s0, 0x1c3f
	s_sub_i32 s0, 0xffffe3c1, s0
	v_rcp_iflag_f32_e32 v2, v2
	s_max_i32 s5, s7, s0
	s_sub_i32 s0, 0, s4
	v_mul_f32_e32 v2, 0x4f7ffffe, v2
	v_cvt_u32_f32_e32 v2, v2
	s_nop 0
	v_readfirstlane_b32 s8, v2
	s_mul_i32 s0, s0, s8
	s_mul_hi_u32 s0, s8, s0
	s_add_i32 s8, s8, s0
	s_cmp_gt_i32 s11, 0xabff
	s_cbranch_scc0 .LBB0_164
	s_cmp_lt_u32 s98, 0xfffefe00
	s_cbranch_scc0 .LBB0_660
	s_add_i32 s0, s11, 0xfe00
	s_and_b32 s1, s0, 0xffff
	s_add_i32 s2, 0, 0x27c28
	s_mulk_i32 s1, 0x487f
	v_mov_b32_e32 v2, s2
	s_lshr_b32 s1, s1, 21
	ds_read_b64 v[2:3], v2
	s_lshl_b32 s6, s1, 6
	s_mulk_i32 s1, 0x71
	s_sub_i32 s0, s0, s1
	s_lshl_b32 s0, s0, 6
	s_and_b32 s37, s0, 0xffc0
	s_mov_b32 s1, 0
	s_mov_b32 s58, 1
	s_cbranch_execz .LBB0_661
	s_add_i32 s9, 0, 0x27c30
	s_mov_b64 s[0:1], 0x10400000
	s_movk_i32 s20, 0x1c30
	s_movk_i32 s30, 0x1000
	s_branch .LBB0_662

; __device__ __forceinline__ void p0_decode(Frame& F, int it, P0Desc& d) {
;     unsigned char* ws = F.ws; int r = it; d.gain = nullptr; d.mode = 0; d.bj = 0;
;     if (r < 4 * P0_I_GU) { const int q = r / P0_I_GU; r -= q * P0_I_GU; d.k0 = 64 * (r / 172); d.n0 = 64 * (r % 172); d.K = DM; d.ldt = 0; d.N = FF; d.mode = 2; d.bj = q & 1;
;         d.W = q == 0 ? INP(2) : q == 1 ? INP(3) : q == 2 ? INP(18) : INP(19); d.gain = q < 2 ? INP(1) : INP(17); d.WT = (bf16_t*)(ws + (q < 2 ? WS_WGU1 : WS_WGU2)); return; }
;     r -= 4 * P0_I_GU;
;     if (r < 2 * P0_I_D) { const int q = r / P0_I_D; r -= q * P0_I_D; d.k0 = 64 * (r / 64); d.n0 = 64 * (r % 64); d.K = FF; d.ldt = 0; d.N = DM; d.W = q == 0 ? INP(4) : INP(20); d.WT = (bf16_t*)(ws + (q == 0 ? WS_WD1 : WS_WD2)); return; }
;     r -= 2 * P0_I_D;
;     if (r < P0_I_IN) { d.k0 = 64 * (r / 113); d.n0 = 64 * (r % 113); d.K = DM; d.ldt = 0; d.N = NIN; d.mode = 1; d.W = INP(6); d.gain = INP(5); d.WT = (bf16_t*)(ws + WS_WIN); return; }
.LBB0_165:
	s_mul_hi_i32 s0, s11, 0x2fa0be83
	s_lshr_b32 s1, s0, 31
	s_ashr_i32 s0, s0, 11
	s_add_i32 s0, s0, s1
	s_mul_i32 s1, s0, 0xffffd500
	s_add_i32 s1, s1, s11
	s_mul_hi_i32 s2, s1, 0x2fa0be83
	s_lshr_b32 s3, s2, 31
	s_ashr_i32 s2, s2, 5
	s_add_i32 s2, s2, s3
	s_lshl_b32 s6, s2, 6
	s_mulk_i32 s2, 0xac
	s_sub_i32 s1, s1, s2
	s_lshl_b32 s37, s1, 6
	s_and_b32 s61, s0, 1
	s_add_i32 s0, s98, 0x12cff
	s_add_i32 s1, s98, 0xd700
	s_add_i32 s2, s98, 0xac00
	s_cmpk_lt_u32 s2, 0x2b00
	s_mov_b32 s2, 0x27c90
	s_cselect_b32 s2, s2, 0x27c98
	s_cmpk_gt_u32 s1, 0x2aff
	s_cselect_b32 s1, s2, 0x27c18
	s_cmpk_gt_u32 s0, 0x55fe
	s_cselect_b32 s0, s1, 0x27c10
	s_add_i32 s9, s0, 0
	s_cmpk_lt_i32 s11, 0x5600
	s_mov_b32 s1, 0x27c08
	s_mov_b32 s0, 0x200000
	s_cselect_b32 s1, s1, 0x27c88
	s_cselect_b32 s0, s0, 0x15e00000
	s_add_i32 s1, s1, 0
	s_waitcnt lgkmcnt(0)
	v_mov_b32_e32 v2, s1
	ds_read_b64 v[2:3], v2
	s_movk_i32 s20, 0x2b00
	s_mov_b32 s1, 0
	s_movk_i32 s30, 0x1000
	s_mov_b32 s58, 2

; #define LAS __attribute__((address_space(3)))
; __device__ __forceinline__ void gu_strip(Frame& F, int uidx, int par) {
;     const int lane = (F.tid & 63), kr = lane >> 3, nq = lane & 7;
;     const int q = uidx < GU_UNITS_GU ? uidx / 344 : 4, nb = uidx < GU_UNITS_GU ? uidx % 344 : uidx - GU_UNITS_GU;
;     const int nkt = q < 4 ? 32 : 86, it0 = q * P0_I_GU + nb, its = q < 4 ? 344 : 128;
;     LAS unsigned* T = (LAS unsigned*)(F.lds + F.wave * 16384);
;     LAS float* part = (LAS float*)(F.lds + 131072 + 1024 * (par & 1));
;     GUDesc d; gu_decode(F, it0, d);
;     f32x4 cm = {0.f, 0.f, 0.f, 0.f};
;     for (int kt = F.wave; kt < nkt; kt += 8) {
; __device__ __forceinline__ void gu_strips(Frame& F, int lo, int hi, int worker, int nworkers) {
;     int par = 0;
;     for (int u = lo + worker; u < hi; u += nworkers, ++par) gu_strip(F, u, par);
; }
.LBB0_1071:
	s_cmpk_gt_i32 s65, 0x2af
	s_cbranch_scc1 .LBB0_1101
	s_waitcnt vmcnt(1)
	v_mbcnt_lo_u32_b32 v2, -1, 0
	v_mbcnt_hi_u32_b32 v2, -1, v2
	s_waitcnt lgkmcnt(0)
	v_and_b32_e32 v4, 64, v2
	v_xor_b32_e32 v3, 8, v2
	v_add_u32_e32 v4, 64, v4
	v_cmp_lt_i32_e32 vcc, v3, v4
	s_add_u32 s11, s78, 0x26000000
	s_addc_u32 s28, s79, 0
	v_cndmask_b32_e32 v3, v2, v3, vcc
	v_lshlrev_b32_e32 v36, 2, v3
	v_xor_b32_e32 v3, 16, v2
	v_cmp_lt_i32_e32 vcc, v3, v4
	s_cmpk_lt_u32 s70, 0x800
	v_lshrrev_b32_e32 v39, 3, v1
	v_cndmask_b32_e32 v3, v2, v3, vcc
	v_lshlrev_b32_e32 v37, 2, v3
	v_xor_b32_e32 v3, 32, v2
	v_cmp_lt_i32_e32 vcc, v3, v4
	v_and_b32_e32 v4, 7, v0
	s_cselect_b64 s[12:13], -1, 0
	v_cndmask_b32_e32 v3, v2, v3, vcc
	s_cmp_lt_u32 s70, 64
	v_lshlrev_b32_e32 v38, 2, v3
	v_lshlrev_b32_e32 v3, 2, v2
	s_cselect_b64 s[4:5], -1, 0
	v_lshrrev_b32_e32 v5, 1, v0
	v_lshlrev_b32_e32 v2, 2, v0
	v_lshlrev_b32_e32 v6, 4, v39
	s_movk_i32 s0, 0x100
	v_lshlrev_b32_e32 v20, 4, v4
	s_lshl_b32 s29, s68, 7
	v_cmp_gt_u32_e64 s[2:3], 8, v1
	v_lshlrev_b32_e32 v40, 2, v4
	v_and_b32_e32 v2, 28, v2
	v_mov_b32_e32 v19, 0
	v_and_or_b32 v41, v3, s0, v6
	v_lshl_add_u32 v3, v39, 2, s33
	v_mul_u32_u24_e32 v4, 0x210, v4
	v_mul_u32_u24_e32 v6, 0x84, v39
	v_add_u32_e32 v7, s33, v20
	v_and_or_b32 v52, v5, 28, s29
	v_cndmask_b32_e64 v5, 0, 1, s[12:13]
	s_mov_b32 s1, 0
	s_and_b64 s[14:15], s[2:3], s[4:5]
	v_or_b32_e32 v42, 4, v41
	v_or_b32_e32 v43, 8, v41
	v_or_b32_e32 v44, 12, v41
	v_or_b32_e32 v45, 0x80, v41
	v_or_b32_e32 v46, 0x84, v41
	v_or_b32_e32 v47, 0x88, v41
	v_or_b32_e32 v48, 0x8c, v41
	v_or_b32_e32 v49, 8, v39
	v_or_b32_e32 v50, 16, v39
	v_or_b32_e32 v51, 24, v39
	v_mov_b32_e32 v21, v19
	s_add_i32 s30, s68, -8
	v_or_b32_e32 v53, s29, v1
	s_mov_b32 s31, 0x27c90
	s_mov_b32 s33, 0x600000
	s_mov_b32 s34, 0x200000
	s_mov_b32 s35, 0x27c08
	s_mov_b32 s36, 0x27ca0
	s_mov_b32 s37, 0x660000
	s_mov_b32 s38, 0x20a00000
	s_movk_i32 s39, 0x7d
	s_movk_i32 s40, 0x7e
	s_movk_i32 s41, 0x7f
	s_mov_b32 s42, 0x42fe0000
	v_add_u32_e32 v54, v3, v4
	v_add_u32_e32 v55, v7, v6
	v_cmp_ne_u32_e64 s[4:5], 1, v5
	s_waitcnt vmcnt(0)
	v_lshlrev_b32_e32 v22, 2, v2
	v_mov_b32_e32 v56, 0x67
	v_mov_b32_e32 v57, 0x6f
	v_mov_b32_e32 v58, 0x77
	v_mov_b32_e32 v59, 0x7f
	s_mov_b32 s43, s65
	s_cmp_eq_u32 s71, 0x100
	s_cbranch_scc0 .Lmy_bal4
	s_add_i32 s43, s65, 0xb0
	s_and_b32 s43, s43, 0xff
.Lmy_bal4:
	s_mov_b32 s44, 0
	s_branch .LBB0_1074
